# FFN-down epilogue de-serialised: y1/stats loads of batches 1 and 3 issued with batches 0 and 2 into free registers (2 instead of 4 dependent round trips); on top of WIN-epilogue fix + v36
# baseline (speedup 1.0000x reference)
; #define PG8_STAGE(bufoff, gbase, voff) do { _Pragma("unroll") for (int _i = 0; _i < 2; ++_i) \
;         __builtin_amdgcn_global_load_lds((const unsigned*)((const char*)(gbase) + (size_t)_i * p##voff + (voff)), (LAS unsigned*)(lds + (bufoff) + ldsw + _i * 8192), 16, 0, 0); } while (0)
; #define PG8_LDA(dst, b, h) do { _Pragma("unroll") for (int m = 0; m < 4; ++m) _Pragma("unroll") for (int k = 0; k < 2; ++k) dst[m][k] = *(const LAS bf16x8*)(lds + PG8_SA(b, h) + aoff + m * 2048 + k * 1024); } while (0)
; #define PG8_LDB(dst, b, h) do { _Pragma("unroll") for (int n = 0; n < 2; ++n) _Pragma("unroll") for (int k = 0; k < 2; ++k) dst[n][k] = *(const LAS bf16x8*)(lds + PG8_SB(b, h) + boff + n * 2048 + k * 1024); } while (0)
; #define PG8_WAIT_V(n) asm volatile("s_waitcnt vmcnt(" #n ")" ::: "memory")
; #define PG8_WAIT_L(n) asm volatile("s_waitcnt lgkmcnt(" #n ")" ::: "memory")
; #define PG8_BAR __builtin_amdgcn_s_barrier()
; #define PG8_SCHED __builtin_amdgcn_sched_barrier(0)
;     ...
;             PG8_LDB(B0, 0, 0); PG8_LDB(B1, 0, 1); PG8_SCHED; PG8_LDA(At, 0, 0); PG8_STAGE(PG8_SA(1, 1), a1 + hstepA, voffA);
;             PG8_WAIT_V(8); PG8_WAIT_L(0); PG8_BAR; PG8_MMA(0, 0, At, B0); PG8_MMA(0, 1, At, B1); PG8_BAR; PG8_SCHED;
;             PG8_LDA(At, 0, 1); PG8_STAGE(PG8_SB(0, 0), b2, voffB); PG8_STAGE(PG8_SB(0, 1), b2 + hstepB, voffB); PG8_STAGE(PG8_SA(0, 0), a2, voffA);
;             PG8_WAIT_V(8); PG8_WAIT_L(0); PG8_BAR; PG8_MMA(1, 0, At, B0); PG8_MMA(1, 1, At, B1); PG8_BAR; PG8_SCHED;
.LBB0_1281:
	ds_read_b128 v[142:145], v188
	ds_read_b128 v[146:149], v188 offset:1024
	ds_read_b128 v[150:153], v188 offset:2048
	ds_read_b128 v[154:157], v188 offset:3072
	ds_read_b128 v[158:161], v189
	ds_read_b128 v[162:165], v189 offset:1024
	ds_read_b128 v[166:169], v189 offset:2048
	ds_read_b128 v[170:173], v189 offset:3072
	s_add_u32 s50, s44, s48
	s_addc_u32 s51, s45, s49
	s_add_u32 s83, s50, 0x10000
	s_addc_u32 s86, s51, 0
	s_add_u32 s50, s50, 0x18000
	s_addc_u32 s51, s51, 0
	s_cmp_eq_u32 s48, 0x7f0000
	s_cselect_b32 s51, s79, s51
	s_cselect_b32 s50, s78, s50
	s_cselect_b32 s85, s35, s81
	s_cselect_b32 s84, s47, s80
	s_cselect_b32 s87, s37, s86
	s_cselect_b32 s86, s43, s83
	v_lshl_add_u64 v[212:213], v[140:141], 0, s[48:49]
	s_mov_b64 s[88:89], 0xc000
	v_lshl_add_u64 v[214:215], v[212:213], 0, s[88:89]
	s_add_i32 m0, s57, 0xc000
	s_mov_b64 s[88:89], 0xe000
	ds_read_b128 v[174:177], v190
	ds_read_b128 v[178:181], v190 offset:1024
	ds_read_b128 v[182:185], v190 offset:2048
	ds_read_b128 v[192:195], v190 offset:3072
	ds_read_b128 v[196:199], v190 offset:4096
	ds_read_b128 v[200:203], v190 offset:5120
	ds_read_b128 v[204:207], v190 offset:6144
	ds_read_b128 v[208:211], v190 offset:7168
	global_load_lds_dwordx4 v[214:215], off
	v_lshl_add_u64 v[212:213], v[212:213], 0, s[88:89]
	s_add_i32 m0, s57, 0xe000
	s_nop 0
	global_load_lds_dwordx4 v[212:213], off
	s_waitcnt vmcnt(8)
	s_waitcnt lgkmcnt(0)
	s_barrier
	s_setprio 1
	s_waitcnt lgkmcnt(0)
	v_mfma_f32_16x16x32_bf16 v[124:127], v[142:145], v[174:177], v[124:127]
	v_mfma_f32_16x16x32_bf16 v[124:127], v[146:149], v[178:181], v[124:127]
	v_mfma_f32_16x16x32_bf16 v[120:123], v[150:153], v[174:177], v[120:123]
	v_mfma_f32_16x16x32_bf16 v[120:123], v[154:157], v[178:181], v[120:123]
	v_mfma_f32_16x16x32_bf16 v[116:119], v[142:145], v[182:185], v[116:119]
	v_mfma_f32_16x16x32_bf16 v[116:119], v[146:149], v[192:195], v[116:119]
	v_mfma_f32_16x16x32_bf16 v[112:115], v[150:153], v[182:185], v[112:115]
	v_mfma_f32_16x16x32_bf16 v[112:115], v[154:157], v[192:195], v[112:115]
	v_mfma_f32_16x16x32_bf16 v[108:111], v[142:145], v[196:199], v[108:111]
	v_mfma_f32_16x16x32_bf16 v[108:111], v[146:149], v[200:203], v[108:111]
	v_mfma_f32_16x16x32_bf16 v[104:107], v[150:153], v[196:199], v[104:107]
	v_mfma_f32_16x16x32_bf16 v[104:107], v[154:157], v[200:203], v[104:107]
	v_mfma_f32_16x16x32_bf16 v[100:103], v[142:145], v[204:207], v[100:103]
	v_mfma_f32_16x16x32_bf16 v[100:103], v[146:149], v[208:211], v[100:103]
	v_mfma_f32_16x16x32_bf16 v[96:99], v[150:153], v[204:207], v[96:99]
	v_mfma_f32_16x16x32_bf16 v[96:99], v[154:157], v[208:211], v[96:99]
	s_setprio 0
	s_setprio 1
	v_mfma_f32_16x16x32_bf16 v[60:63], v[158:161], v[174:177], v[60:63]
	v_mfma_f32_16x16x32_bf16 v[60:63], v[162:165], v[178:181], v[60:63]
	v_mfma_f32_16x16x32_bf16 v[56:59], v[166:169], v[174:177], v[56:59]
	v_mfma_f32_16x16x32_bf16 v[56:59], v[170:173], v[178:181], v[56:59]
	v_mfma_f32_16x16x32_bf16 v[52:55], v[158:161], v[182:185], v[52:55]
	v_mfma_f32_16x16x32_bf16 v[52:55], v[162:165], v[192:195], v[52:55]
	v_mfma_f32_16x16x32_bf16 v[48:51], v[166:169], v[182:185], v[48:51]
	v_mfma_f32_16x16x32_bf16 v[48:51], v[170:173], v[192:195], v[48:51]
	v_mfma_f32_16x16x32_bf16 v[44:47], v[158:161], v[196:199], v[44:47]
	v_mfma_f32_16x16x32_bf16 v[44:47], v[162:165], v[200:203], v[44:47]
	v_mfma_f32_16x16x32_bf16 v[40:43], v[166:169], v[196:199], v[40:43]
	v_mfma_f32_16x16x32_bf16 v[40:43], v[170:173], v[200:203], v[40:43]
	v_mfma_f32_16x16x32_bf16 v[36:39], v[158:161], v[204:207], v[36:39]
	v_mfma_f32_16x16x32_bf16 v[36:39], v[162:165], v[208:211], v[36:39]
	v_mfma_f32_16x16x32_bf16 v[32:35], v[166:169], v[204:207], v[32:35]
	v_mfma_f32_16x16x32_bf16 v[32:35], v[170:173], v[208:211], v[32:35]
	s_setprio 0
	s_barrier
	s_add_i32 s83, s94, s56
	v_lshl_add_u64 v[212:213], s[84:85], 0, v[130:131]
	s_mov_b32 m0, s83
	ds_read_b128 v[174:177], v190 offset:16384
	ds_read_b128 v[178:181], v190 offset:17408
	ds_read_b128 v[182:185], v190 offset:18432
	ds_read_b128 v[192:195], v190 offset:19456
	ds_read_b128 v[196:199], v190 offset:20480
	ds_read_b128 v[200:203], v190 offset:21504
	ds_read_b128 v[204:207], v190 offset:22528
	ds_read_b128 v[208:211], v190 offset:23552
	global_load_lds_dwordx4 v[212:213], off
	v_lshl_add_u64 v[214:215], v[212:213], 0, s[4:5]
	s_add_i32 m0, s83, 0x2000
	s_add_i32 s83, s95, s56
	global_load_lds_dwordx4 v[214:215], off
	v_lshl_add_u64 v[214:215], v[212:213], 0, s[6:7]
	s_mov_b32 m0, s83
	s_nop 0
	global_load_lds_dwordx4 v[214:215], off
	v_lshl_add_u64 v[214:215], v[212:213], 0, s[8:9]
	s_add_i32 m0, s83, 0x2000
	s_nop 0
	global_load_lds_dwordx4 v[214:215], off
	v_lshl_add_u64 v[214:215], s[86:87], 0, v[128:129]
	s_mov_b32 m0, s57
	v_lshl_add_u64 v[216:217], v[214:215], 0, s[10:11]
	global_load_lds_dwordx4 v[214:215], off
	s_mov_b32 m0, s58
	s_nop 0
	global_load_lds_dwordx4 v[216:217], off
	s_waitcnt vmcnt(8)
	s_waitcnt lgkmcnt(0)
	s_barrier
; #define PG8_STAGE(bufoff, gbase, voff) do { _Pragma("unroll") for (int _i = 0; _i < 2; ++_i) \
;         __builtin_amdgcn_global_load_lds((const unsigned*)((const char*)(gbase) + (size_t)_i * p##voff + (voff)), (LAS unsigned*)(lds + (bufoff) + ldsw + _i * 8192), 16, 0, 0); } while (0)
; #define PG8_LDA(dst, b, h) do { _Pragma("unroll") for (int m = 0; m < 4; ++m) _Pragma("unroll") for (int k = 0; k < 2; ++k) dst[m][k] = *(const LAS bf16x8*)(lds + PG8_SA(b, h) + aoff + m * 2048 + k * 1024); } while (0)
; #define PG8_LDB(dst, b, h) do { _Pragma("unroll") for (int n = 0; n < 2; ++n) _Pragma("unroll") for (int k = 0; k < 2; ++k) dst[n][k] = *(const LAS bf16x8*)(lds + PG8_SB(b, h) + boff + n * 2048 + k * 1024); } while (0)
; #define PG8_WAIT_V(n) asm volatile("s_waitcnt vmcnt(" #n ")" ::: "memory")
; #define PG8_WAIT_L(n) asm volatile("s_waitcnt lgkmcnt(" #n ")" ::: "memory")
; #define PG8_BAR __builtin_amdgcn_s_barrier()
; #define PG8_SCHED __builtin_amdgcn_sched_barrier(0)
;     ...
;             PG8_WAIT_V(8); PG8_WAIT_L(0); PG8_BAR; PG8_MMA(1, 0, At, B0); PG8_MMA(1, 1, At, B1); PG8_BAR; PG8_SCHED;
;             PG8_LDB(B0, 1, 0); PG8_LDB(B1, 1, 1); PG8_SCHED; PG8_LDA(At, 1, 0); PG8_STAGE(PG8_SA(0, 1), a2 + hstepA, voffA);
;             PG8_WAIT_V(8); PG8_WAIT_L(0); PG8_BAR; PG8_MMA(0, 0, At, B0); PG8_MMA(0, 1, At, B1); PG8_BAR; PG8_SCHED;
;             PG8_LDA(At, 1, 1); PG8_STAGE(PG8_SB(1, 0), b3, voffB); PG8_STAGE(PG8_SB(1, 1), b3 + hstepB, voffB); PG8_STAGE(PG8_SA(1, 0), a3, voffA);
	s_setprio 1
	s_waitcnt lgkmcnt(0)
	v_mfma_f32_16x16x32_bf16 v[92:95], v[142:145], v[174:177], v[92:95]
	v_mfma_f32_16x16x32_bf16 v[92:95], v[146:149], v[178:181], v[92:95]
	v_mfma_f32_16x16x32_bf16 v[88:91], v[150:153], v[174:177], v[88:91]
	v_mfma_f32_16x16x32_bf16 v[88:91], v[154:157], v[178:181], v[88:91]
	v_mfma_f32_16x16x32_bf16 v[84:87], v[142:145], v[182:185], v[84:87]
	v_mfma_f32_16x16x32_bf16 v[84:87], v[146:149], v[192:195], v[84:87]
	v_mfma_f32_16x16x32_bf16 v[80:83], v[150:153], v[182:185], v[80:83]
	v_mfma_f32_16x16x32_bf16 v[80:83], v[154:157], v[192:195], v[80:83]
	v_mfma_f32_16x16x32_bf16 v[76:79], v[142:145], v[196:199], v[76:79]
	v_mfma_f32_16x16x32_bf16 v[76:79], v[146:149], v[200:203], v[76:79]
	v_mfma_f32_16x16x32_bf16 v[72:75], v[150:153], v[196:199], v[72:75]
	v_mfma_f32_16x16x32_bf16 v[72:75], v[154:157], v[200:203], v[72:75]
	v_mfma_f32_16x16x32_bf16 v[68:71], v[142:145], v[204:207], v[68:71]
	v_mfma_f32_16x16x32_bf16 v[68:71], v[146:149], v[208:211], v[68:71]
	v_mfma_f32_16x16x32_bf16 v[64:67], v[150:153], v[204:207], v[64:67]
	v_mfma_f32_16x16x32_bf16 v[64:67], v[154:157], v[208:211], v[64:67]
	s_setprio 0
	s_setprio 1
	v_mfma_f32_16x16x32_bf16 v[28:31], v[158:161], v[174:177], v[28:31]
	v_mfma_f32_16x16x32_bf16 v[28:31], v[162:165], v[178:181], v[28:31]
	v_mfma_f32_16x16x32_bf16 v[24:27], v[166:169], v[174:177], v[24:27]
	v_mfma_f32_16x16x32_bf16 v[24:27], v[170:173], v[178:181], v[24:27]
	v_mfma_f32_16x16x32_bf16 v[20:23], v[158:161], v[182:185], v[20:23]
	v_mfma_f32_16x16x32_bf16 v[20:23], v[162:165], v[192:195], v[20:23]
	v_mfma_f32_16x16x32_bf16 v[16:19], v[166:169], v[182:185], v[16:19]
	v_mfma_f32_16x16x32_bf16 v[16:19], v[170:173], v[192:195], v[16:19]
	v_mfma_f32_16x16x32_bf16 v[12:15], v[158:161], v[196:199], v[12:15]
	v_mfma_f32_16x16x32_bf16 v[12:15], v[162:165], v[200:203], v[12:15]
	v_mfma_f32_16x16x32_bf16 v[8:11], v[166:169], v[196:199], v[8:11]
	v_mfma_f32_16x16x32_bf16 v[8:11], v[170:173], v[200:203], v[8:11]
	v_mfma_f32_16x16x32_bf16 v[4:7], v[158:161], v[204:207], v[4:7]
	v_mfma_f32_16x16x32_bf16 v[4:7], v[162:165], v[208:211], v[4:7]
	v_mfma_f32_16x16x32_bf16 v[0:3], v[166:169], v[204:207], v[0:3]
	v_mfma_f32_16x16x32_bf16 v[0:3], v[170:173], v[208:211], v[0:3]
	s_setprio 0
	s_barrier
	s_add_i32 s83, 0, 0x18000
	v_add_u32_e32 v132, s83, v187
	s_add_i32 s84, 0, 0x1c000
	ds_read_b128 v[142:145], v132
	ds_read_b128 v[146:149], v132 offset:1024
	ds_read_b128 v[150:153], v132 offset:2048
	ds_read_b128 v[154:157], v132 offset:3072
	v_add_u32_e32 v132, s84, v187
	ds_read_b128 v[158:161], v132
	ds_read_b128 v[162:165], v132 offset:1024
	ds_read_b128 v[166:169], v132 offset:2048
	ds_read_b128 v[170:173], v132 offset:3072
	s_mov_b32 m0, s59
	v_lshl_add_u64 v[216:217], v[214:215], 0, s[12:13]
	ds_read_b128 v[174:177], v190 offset:32768
	ds_read_b128 v[178:181], v190 offset:33792
	ds_read_b128 v[182:185], v190 offset:34816
	ds_read_b128 v[192:195], v190 offset:35840
	ds_read_b128 v[196:199], v190 offset:36864
	ds_read_b128 v[200:203], v190 offset:37888
	ds_read_b128 v[204:207], v190 offset:38912
	ds_read_b128 v[208:211], v190 offset:39936
	global_load_lds_dwordx4 v[216:217], off
	v_lshl_add_u64 v[214:215], v[214:215], 0, s[14:15]
	s_mov_b32 m0, s60
	s_nop 0
	global_load_lds_dwordx4 v[214:215], off
	s_waitcnt vmcnt(8)
	s_waitcnt lgkmcnt(0)
	s_barrier
	s_setprio 1
	s_waitcnt lgkmcnt(0)
	v_mfma_f32_16x16x32_bf16 v[124:127], v[142:145], v[174:177], v[124:127]
	v_mfma_f32_16x16x32_bf16 v[124:127], v[146:149], v[178:181], v[124:127]
	v_mfma_f32_16x16x32_bf16 v[120:123], v[150:153], v[174:177], v[120:123]
	v_mfma_f32_16x16x32_bf16 v[120:123], v[154:157], v[178:181], v[120:123]
	v_mfma_f32_16x16x32_bf16 v[116:119], v[142:145], v[182:185], v[116:119]
	v_mfma_f32_16x16x32_bf16 v[116:119], v[146:149], v[192:195], v[116:119]
	v_mfma_f32_16x16x32_bf16 v[112:115], v[150:153], v[182:185], v[112:115]
	v_mfma_f32_16x16x32_bf16 v[112:115], v[154:157], v[192:195], v[112:115]
	v_mfma_f32_16x16x32_bf16 v[108:111], v[142:145], v[196:199], v[108:111]
	v_mfma_f32_16x16x32_bf16 v[108:111], v[146:149], v[200:203], v[108:111]
	v_mfma_f32_16x16x32_bf16 v[104:107], v[150:153], v[196:199], v[104:107]
	v_mfma_f32_16x16x32_bf16 v[104:107], v[154:157], v[200:203], v[104:107]
	v_mfma_f32_16x16x32_bf16 v[100:103], v[142:145], v[204:207], v[100:103]
	v_mfma_f32_16x16x32_bf16 v[100:103], v[146:149], v[208:211], v[100:103]
	v_mfma_f32_16x16x32_bf16 v[96:99], v[150:153], v[204:207], v[96:99]
	v_mfma_f32_16x16x32_bf16 v[96:99], v[154:157], v[208:211], v[96:99]
	s_setprio 0
	s_setprio 1
	v_mfma_f32_16x16x32_bf16 v[60:63], v[158:161], v[174:177], v[60:63]
	v_mfma_f32_16x16x32_bf16 v[60:63], v[162:165], v[178:181], v[60:63]
	v_mfma_f32_16x16x32_bf16 v[56:59], v[166:169], v[174:177], v[56:59]
	v_mfma_f32_16x16x32_bf16 v[56:59], v[170:173], v[178:181], v[56:59]
	v_mfma_f32_16x16x32_bf16 v[52:55], v[158:161], v[182:185], v[52:55]
	v_mfma_f32_16x16x32_bf16 v[52:55], v[162:165], v[192:195], v[52:55]
	v_mfma_f32_16x16x32_bf16 v[48:51], v[166:169], v[182:185], v[48:51]
	v_mfma_f32_16x16x32_bf16 v[48:51], v[170:173], v[192:195], v[48:51]
	v_mfma_f32_16x16x32_bf16 v[44:47], v[158:161], v[196:199], v[44:47]
	v_mfma_f32_16x16x32_bf16 v[44:47], v[162:165], v[200:203], v[44:47]
	v_mfma_f32_16x16x32_bf16 v[40:43], v[166:169], v[196:199], v[40:43]
	v_mfma_f32_16x16x32_bf16 v[40:43], v[170:173], v[200:203], v[40:43]
	v_mfma_f32_16x16x32_bf16 v[36:39], v[158:161], v[204:207], v[36:39]
	v_mfma_f32_16x16x32_bf16 v[36:39], v[162:165], v[208:211], v[36:39]
	v_mfma_f32_16x16x32_bf16 v[32:35], v[166:169], v[204:207], v[32:35]
	v_mfma_f32_16x16x32_bf16 v[32:35], v[170:173], v[208:211], v[32:35]
	s_setprio 0
	s_barrier
; #define PG8_STAGE(bufoff, gbase, voff) do { _Pragma("unroll") for (int _i = 0; _i < 2; ++_i) \
;         __builtin_amdgcn_global_load_lds((const unsigned*)((const char*)(gbase) + (size_t)_i * p##voff + (voff)), (LAS unsigned*)(lds + (bufoff) + ldsw + _i * 8192), 16, 0, 0); } while (0)
; #define PG8_LDA(dst, b, h) do { _Pragma("unroll") for (int m = 0; m < 4; ++m) _Pragma("unroll") for (int k = 0; k < 2; ++k) dst[m][k] = *(const LAS bf16x8*)(lds + PG8_SA(b, h) + aoff + m * 2048 + k * 1024); } while (0)
; #define PG8_WAIT_V(n) asm volatile("s_waitcnt vmcnt(" #n ")" ::: "memory")
; #define PG8_WAIT_L(n) asm volatile("s_waitcnt lgkmcnt(" #n ")" ::: "memory")
; #define PG8_BAR __builtin_amdgcn_s_barrier()
; #define PG8_SCHED __builtin_amdgcn_sched_barrier(0)
;     ...
;             PG8_LDA(At, 1, 1); PG8_STAGE(PG8_SB(1, 0), b3, voffB); PG8_STAGE(PG8_SB(1, 1), b3 + hstepB, voffB); PG8_STAGE(PG8_SA(1, 0), a3, voffA);
;             PG8_WAIT_V(8); PG8_WAIT_L(0); PG8_BAR; PG8_MMA(1, 0, At, B0); PG8_MMA(1, 1, At, B1); PG8_BAR; PG8_SCHED;
;         }
;     __device__ __forceinline__ void operator()(const Acc& acc, const Unit& u, int wr, int wc, int fr, int fq) const {
;     ...
;         const int rowb = u.pm * 256 + wr * 64 + fr, col0 = u.pn * 256 + wc * 32 + 8 * fq; const int b = (u.pm * 256) / S;
;         const size_t yb = (((size_t)u.pm * 16 + u.pn) * 256 + (wr * 64 + fr)) * 256 + wc * 32 + 8 * fq;
; #pragma unroll
;         for (int bj = 0; bj < 2; ++bj) {
;             f32x4 gm[2], G[2], Bc[2];
; #pragma unroll
;             for (int n = 0; n < 2; ++n) { const int c = col0 + bj * 128 + n * 4; gm[n] = *(const f32x4*)(gate + (size_t)b * NADA + c) + 1.0f; G[n] = *(const f32x4*)(lg + c) * ALPHA; Bc[n] = *(const f32x4*)(lb + c) * ALPHA; }
; #pragma unroll
;             for (int hf = 0; hf < 2; ++hf) {
;                 u32x4 yv[4]; f32x2 st[4];
; #pragma unroll
;                 for (int m = 0; m < 4; ++m) { const int row = rowb + hf * 128 + m * 16; yv[m] = *(const u32x4*)(y1 + yb + (size_t)(hf * 128 + m * 16) * 256 + bj * 128); st[m] = *(const f32x2*)(stats + (size_t)row * 2); }
	s_add_i32 s83, s83, s56
	v_lshl_add_u64 v[214:215], v[212:213], 0, s[20:21]
	s_mov_b32 m0, s83
	ds_read_b128 v[174:177], v190 offset:49152
	ds_read_b128 v[178:181], v190 offset:50176
	ds_read_b128 v[182:185], v190 offset:51200
	ds_read_b128 v[192:195], v190 offset:52224
	ds_read_b128 v[196:199], v190 offset:53248
	ds_read_b128 v[200:203], v190 offset:54272
	ds_read_b128 v[204:207], v190 offset:55296
	ds_read_b128 v[208:211], v190 offset:56320
	global_load_lds_dwordx4 v[214:215], off
	v_lshl_add_u64 v[214:215], v[212:213], 0, s[22:23]
	s_add_i32 m0, s83, 0x2000
	s_add_i32 s83, s84, s56
	global_load_lds_dwordx4 v[214:215], off
	v_lshl_add_u64 v[214:215], v[212:213], 0, s[24:25]
	s_mov_b32 m0, s83
	v_lshl_add_u64 v[212:213], v[212:213], 0, s[26:27]
	global_load_lds_dwordx4 v[214:215], off
	s_add_i32 m0, s83, 0x2000
	s_nop 0
	global_load_lds_dwordx4 v[212:213], off
	v_lshl_add_u64 v[212:213], s[50:51], 0, v[128:129]
	s_mov_b32 m0, s71
	s_nop 0
	global_load_lds_dwordx4 v[212:213], off
	v_lshl_add_u64 v[212:213], v[212:213], 0, s[10:11]
	s_mov_b32 m0, s72
	s_nop 0
	global_load_lds_dwordx4 v[212:213], off
	s_waitcnt vmcnt(8)
	s_waitcnt lgkmcnt(0)
	s_barrier
	s_setprio 1
	s_waitcnt lgkmcnt(0)
	v_mfma_f32_16x16x32_bf16 v[92:95], v[142:145], v[174:177], v[92:95]
	v_mfma_f32_16x16x32_bf16 v[92:95], v[146:149], v[178:181], v[92:95]
	v_mfma_f32_16x16x32_bf16 v[88:91], v[150:153], v[174:177], v[88:91]
	v_mfma_f32_16x16x32_bf16 v[88:91], v[154:157], v[178:181], v[88:91]
	v_mfma_f32_16x16x32_bf16 v[84:87], v[142:145], v[182:185], v[84:87]
	v_mfma_f32_16x16x32_bf16 v[84:87], v[146:149], v[192:195], v[84:87]
	v_mfma_f32_16x16x32_bf16 v[80:83], v[150:153], v[182:185], v[80:83]
	v_mfma_f32_16x16x32_bf16 v[80:83], v[154:157], v[192:195], v[80:83]
	v_mfma_f32_16x16x32_bf16 v[76:79], v[142:145], v[196:199], v[76:79]
	v_mfma_f32_16x16x32_bf16 v[76:79], v[146:149], v[200:203], v[76:79]
	v_mfma_f32_16x16x32_bf16 v[72:75], v[150:153], v[196:199], v[72:75]
	v_mfma_f32_16x16x32_bf16 v[72:75], v[154:157], v[200:203], v[72:75]
	v_mfma_f32_16x16x32_bf16 v[68:71], v[142:145], v[204:207], v[68:71]
	v_mfma_f32_16x16x32_bf16 v[68:71], v[146:149], v[208:211], v[68:71]
	v_mfma_f32_16x16x32_bf16 v[64:67], v[150:153], v[204:207], v[64:67]
	v_mfma_f32_16x16x32_bf16 v[64:67], v[154:157], v[208:211], v[64:67]
	s_setprio 0
	s_setprio 1
	v_mfma_f32_16x16x32_bf16 v[28:31], v[158:161], v[174:177], v[28:31]
	v_mfma_f32_16x16x32_bf16 v[28:31], v[162:165], v[178:181], v[28:31]
	v_mfma_f32_16x16x32_bf16 v[24:27], v[166:169], v[174:177], v[24:27]
	v_mfma_f32_16x16x32_bf16 v[24:27], v[170:173], v[178:181], v[24:27]
	v_mfma_f32_16x16x32_bf16 v[20:23], v[158:161], v[182:185], v[20:23]
	v_mfma_f32_16x16x32_bf16 v[20:23], v[162:165], v[192:195], v[20:23]
	v_mfma_f32_16x16x32_bf16 v[16:19], v[166:169], v[182:185], v[16:19]
	v_mfma_f32_16x16x32_bf16 v[16:19], v[170:173], v[192:195], v[16:19]
	v_mfma_f32_16x16x32_bf16 v[12:15], v[158:161], v[196:199], v[12:15]
	v_mfma_f32_16x16x32_bf16 v[12:15], v[162:165], v[200:203], v[12:15]
	v_mfma_f32_16x16x32_bf16 v[8:11], v[166:169], v[196:199], v[8:11]
	v_mfma_f32_16x16x32_bf16 v[8:11], v[170:173], v[200:203], v[8:11]
	v_mfma_f32_16x16x32_bf16 v[4:7], v[158:161], v[204:207], v[4:7]
	v_mfma_f32_16x16x32_bf16 v[4:7], v[162:165], v[208:211], v[4:7]
	v_mfma_f32_16x16x32_bf16 v[0:3], v[166:169], v[204:207], v[0:3]
	v_mfma_f32_16x16x32_bf16 v[0:3], v[170:173], v[208:211], v[0:3]
	s_setprio 0
	s_barrier
	s_add_i32 s82, s82, 2
	s_add_u32 s80, s80, 0x100
	s_addc_u32 s81, s81, 0
	s_add_u32 s48, s48, 0x10000
	s_addc_u32 s49, s49, 0
	s_cmpk_gt_u32 s82, 0xfd
	s_cbranch_scc0 .LBB0_1281
	s_lshl_b32 s37, s46, 8
	v_lshrrev_b32_e32 v132, 1, v191
	s_or_b32 s37, s37, s74
	v_and_b32_e32 v141, 56, v132
	s_ashr_i32 s43, s42, 31
	v_add_u32_e32 v140, s37, v141
	s_lshr_b32 s37, s43, 28
	s_lshl_b32 s35, s42, 8
	s_add_i32 s37, s42, s37
	s_ashr_i32 s47, s46, 31
	s_add_i32 s35, s35, s73
	s_ashr_i32 s37, s37, 4
	s_lshl_b64 s[42:43], s[42:43], 12
	s_lshl_b64 s[44:45], s[46:47], 8
	v_and_b32_e32 v150, 15, v191
	s_add_u32 s42, s42, s44
	s_addc_u32 s43, s43, s45
	v_or_b32_e32 v132, s73, v150
	v_lshl_add_u64 v[148:149], s[42:43], 0, v[132:133]
	s_mul_hi_i32 s43, s37, 0x18000
	s_mul_i32 s37, s37, 0x18000
	v_add_u32_e32 v132, s74, v141
	v_ashrrev_i32_e32 v141, 31, v140
	v_readlane_b32 s76, v245, 10
	s_add_u32 s42, s69, s37
	v_lshlrev_b64 v[220:221], 9, v[148:149]
	v_or_b32_e32 v154, s35, v150
	v_lshlrev_b64 v[140:141], 2, v[140:141]
	v_readlane_b32 s78, v245, 12
	v_readlane_b32 s79, v245, 13
	v_readlane_b32 s80, v245, 14
	v_readlane_b32 s81, v245, 15
	s_addc_u32 s43, s70, s43
	v_lshl_or_b32 v220, v132, 1, v220
	v_ashrrev_i32_e32 v155, 31, v154
	v_lshl_add_u64 v[142:143], s[78:79], 0, v[140:141]
	v_lshl_add_u64 v[144:145], s[80:81], 0, v[140:141]
	v_lshl_add_u64 v[146:147], s[42:43], 0, v[140:141]
	v_lshl_add_u64 v[148:149], s[16:17], 0, v[220:221]
	v_lshl_add_u64 v[140:141], v[154:155], 3, s[18:19]
	global_load_dwordx4 v[164:167], v[142:143], off offset:16
	global_load_dwordx4 v[168:171], v[142:143], off
	global_load_dwordx4 v[182:185], v[144:145], off offset:16
	global_load_dwordx4 v[192:195], v[144:145], off
	global_load_dwordx4 v[196:199], v[146:147], off offset:16
	global_load_dwordx4 v[200:203], v[146:147], off
	global_load_dwordx4 v[204:207], v[148:149], off
	global_load_dwordx2 v[222:223], v[140:141], off
	v_or_b32_e32 v152, 16, v154
	v_add_co_u32_e32 v150, vcc, s66, v148
	v_ashrrev_i32_e32 v153, 31, v152
	s_nop 0
	v_addc_co_u32_e32 v151, vcc, 0, v149, vcc
	v_lshl_add_u64 v[152:153], v[152:153], 3, s[18:19]
	global_load_dwordx4 v[208:211], v[150:151], off
	global_load_dwordx2 v[224:225], v[152:153], off
; __device__ __forceinline__ u32x4 pack8f(f32x4 lo, f32x4 hi) { u32x4 w; w.x = cvtpk(lo[0], lo[1]); w.y = cvtpk(lo[2], lo[3]); w.z = cvtpk(hi[0], hi[1]); w.w = cvtpk(hi[2], hi[3]); return w; }
;     __device__ __forceinline__ void operator()(const Acc& acc, const Unit& u, int wr, int wc, int fr, int fq) const {
;     ...
;         for (int bj = 0; bj < 2; ++bj) {
;             f32x4 gm[2], G[2], Bc[2];
; #pragma unroll
;             for (int n = 0; n < 2; ++n) { const int c = col0 + bj * 128 + n * 4; gm[n] = *(const f32x4*)(gate + (size_t)b * NADA + c) + 1.0f; G[n] = *(const f32x4*)(lg + c) * ALPHA; Bc[n] = *(const f32x4*)(lb + c) * ALPHA; }
; #pragma unroll
;             for (int hf = 0; hf < 2; ++hf) {
;                 u32x4 yv[4]; f32x2 st[4];
; #pragma unroll
;                 for (int m = 0; m < 4; ++m) { const int row = rowb + hf * 128 + m * 16; yv[m] = *(const u32x4*)(y1 + yb + (size_t)(hf * 128 + m * 16) * 256 + bj * 128); st[m] = *(const f32x2*)(stats + (size_t)row * 2); }
; #pragma unroll
;                 for (int m = 0; m < 4; ++m) { const int row = rowb + hf * 128 + m * 16;
;                     f32x4 lo, hi; unpack8(yv[m], lo, hi); const float r = st[m][1], mr = st[m][0] * r;
;                     lo = (lo * r - mr) * G[0] + Bc[0] + gm[0] * acc[hf][bj][m][0]; hi = (hi * r - mr) * G[1] + Bc[1] + gm[1] * acc[hf][bj][m][1];
;                     *(u32x4*)(y2 + yb + (size_t)(hf * 128 + m * 16) * 256 + bj * 128) = pack8f(lo, hi); }
	v_add_co_u32_e32 v158, vcc, s67, v148
	v_or_b32_e32 v156, 32, v154
	s_nop 0
	v_addc_co_u32_e32 v159, vcc, 0, v149, vcc
	v_or_b32_e32 v154, 48, v154
	v_ashrrev_i32_e32 v157, 31, v156
	global_load_dwordx4 v[212:215], v[158:159], off
	v_ashrrev_i32_e32 v155, 31, v154
	v_lshl_add_u64 v[160:161], v[156:157], 3, s[18:19]
	v_add_co_u32_e32 v156, vcc, s68, v148
	v_lshl_add_u64 v[154:155], v[154:155], 3, s[18:19]
	s_nop 0
	v_addc_co_u32_e32 v157, vcc, 0, v149, vcc
	global_load_dwordx2 v[226:227], v[160:161], off
	global_load_dwordx4 v[216:219], v[156:157], off
	global_load_dwordx2 v[228:229], v[154:155], off
	v_add_co_u32_e32 v242, vcc, s62, v148
	s_nop 1
	v_addc_co_u32_e32 v243, vcc, 0, v149, vcc
	global_load_dwordx4 v[230:233], v[242:243], off
	v_add_co_u32_e32 v242, vcc, s63, v148
	s_nop 1
	v_addc_co_u32_e32 v243, vcc, 0, v149, vcc
	global_load_dwordx4 v[234:237], v[242:243], off
	v_add_co_u32_e32 v242, vcc, s64, v148
	s_nop 1
	v_addc_co_u32_e32 v243, vcc, 0, v149, vcc
	global_load_dwordx4 v[238:241], v[242:243], off
	v_add_co_u32_e32 v242, vcc, s65, v148
	s_nop 1
	v_addc_co_u32_e32 v243, vcc, 0, v149, vcc
	global_load_dwordx4 v[246:249], v[242:243], off
	global_load_dwordx2 v[242:243], v[140:141], off offset:1024
	global_load_dwordx2 v[250:251], v[140:141], off offset:1152
	global_load_dwordx2 v[252:253], v[140:141], off offset:1280
	global_load_dwordx2 v[254:255], v[140:141], off offset:1408
	v_readlane_b32 s42, v245, 61
	v_readlane_b32 s43, v245, 62
	s_mov_b32 s46, s34
	s_mov_b64 s[48:49], s[40:41]
	s_mov_b64 s[44:45], s[38:39]
	v_readlane_b32 s77, v245, 11
	v_readlane_b32 s82, v245, 16
	v_readlane_b32 s83, v245, 17
	v_readlane_b32 s84, v245, 18
	v_readlane_b32 s85, v245, 19
	v_readlane_b32 s86, v245, 20
	v_readlane_b32 s87, v245, 21
	v_readlane_b32 s88, v245, 22
	v_readlane_b32 s89, v245, 23
	v_readlane_b32 s90, v245, 24
	v_readlane_b32 s91, v245, 25
	s_waitcnt vmcnt(8)
	v_pk_mul_f32 v[162:163], v[166:167], s[28:29] op_sel_hi:[1,0]
	v_pk_mul_f32 v[166:167], v[184:185], s[28:29] op_sel_hi:[1,0]
	v_pk_mul_f32 v[178:179], v[194:195], s[28:29] op_sel_hi:[1,0]
	v_pk_mul_f32 v[180:181], v[192:193], s[28:29] op_sel_hi:[1,0]
	v_pk_add_f32 v[184:185], v[200:201], 1.0 op_sel_hi:[1,0]
	v_lshlrev_b32_e32 v192, 16, v204
	v_and_b32_e32 v193, 0xffff0000, v204
	v_lshlrev_b32_e32 v194, 16, v205
	v_and_b32_e32 v195, 0xffff0000, v205
	v_pk_mul_f32 v[200:201], v[222:223], v[222:223] op_sel:[0,1] op_sel_hi:[1,0]
	v_pk_mul_f32 v[174:175], v[170:171], s[28:29] op_sel_hi:[1,0]
	v_pk_mul_f32 v[176:177], v[168:169], s[28:29] op_sel_hi:[1,0]
	v_pk_fma_f32 v[192:193], v[222:223], v[192:193], v[200:201] op_sel:[1,0,0] op_sel_hi:[1,1,0] neg_lo:[0,0,1] neg_hi:[0,0,1]
	v_pk_fma_f32 v[194:195], v[222:223], v[194:195], v[200:201] op_sel:[1,0,0] op_sel_hi:[1,1,0] neg_lo:[0,0,1] neg_hi:[0,0,1]
	v_pk_mul_f32 v[172:173], v[182:183], s[28:29] op_sel_hi:[1,0]
	v_pk_add_f32 v[182:183], v[202:203], 1.0 op_sel_hi:[1,0]
	v_pk_add_f32 v[168:169], v[198:199], 1.0 op_sel_hi:[1,0]
	v_pk_add_f32 v[170:171], v[196:197], 1.0 op_sel_hi:[1,0]
	v_lshlrev_b32_e32 v196, 16, v206
	v_and_b32_e32 v197, 0xffff0000, v206
	v_lshlrev_b32_e32 v198, 16, v207
	v_and_b32_e32 v199, 0xffff0000, v207
	v_pk_fma_f32 v[194:195], v[174:175], v[194:195], v[178:179]
	v_pk_fma_f32 v[192:193], v[176:177], v[192:193], v[180:181]
	v_pk_mul_f32 v[164:165], v[164:165], s[28:29] op_sel_hi:[1,0]
	v_pk_fma_f32 v[126:127], v[126:127], v[182:183], v[194:195]
	v_pk_fma_f32 v[124:125], v[124:125], v[184:185], v[192:193]
	v_pk_fma_f32 v[192:193], v[222:223], v[196:197], v[200:201] op_sel:[1,0,0] op_sel_hi:[1,1,0] neg_lo:[0,0,1] neg_hi:[0,0,1]
	v_pk_fma_f32 v[194:195], v[222:223], v[198:199], v[200:201] op_sel:[1,0,0] op_sel_hi:[1,1,0] neg_lo:[0,0,1] neg_hi:[0,0,1]
	v_pk_fma_f32 v[192:193], v[164:165], v[192:193], v[172:173]
	v_pk_fma_f32 v[194:195], v[162:163], v[194:195], v[166:167]
	v_pk_fma_f32 v[120:121], v[120:121], v[170:171], v[192:193]
	v_pk_fma_f32 v[194:195], v[122:123], v[168:169], v[194:195]
	v_cvt_pk_bf16_f32 v122, v124, v125
	v_cvt_pk_bf16_f32 v123, v126, v127
	v_cvt_pk_bf16_f32 v124, v120, v121
	v_cvt_pk_bf16_f32 v125, v194, v195
	v_lshl_add_u64 v[120:121], s[42:43], 0, v[220:221]
	global_store_dwordx4 v[120:121], v[122:125], off
	v_pk_mul_f32 v[194:195], v[224:225], v[224:225] op_sel:[0,1] op_sel_hi:[1,0]
	v_lshlrev_b32_e32 v126, 16, v210
	v_lshlrev_b32_e32 v124, 16, v209
	v_and_b32_e32 v125, 0xffff0000, v209
	v_lshlrev_b32_e32 v122, 16, v208
	v_and_b32_e32 v123, 0xffff0000, v208
	v_pk_fma_f32 v[124:125], v[224:225], v[124:125], v[194:195] op_sel:[1,0,0] op_sel_hi:[1,1,0] neg_lo:[0,0,1] neg_hi:[0,0,1]
	v_and_b32_e32 v127, 0xffff0000, v210
	v_pk_fma_f32 v[122:123], v[224:225], v[122:123], v[194:195] op_sel:[1,0,0] op_sel_hi:[1,1,0] neg_lo:[0,0,1] neg_hi:[0,0,1]
	v_pk_fma_f32 v[124:125], v[174:175], v[124:125], v[178:179]
	v_lshlrev_b32_e32 v192, 16, v211
	v_and_b32_e32 v193, 0xffff0000, v211
	v_pk_fma_f32 v[122:123], v[176:177], v[122:123], v[180:181]
	v_pk_fma_f32 v[118:119], v[118:119], v[182:183], v[124:125]
	v_pk_fma_f32 v[124:125], v[224:225], v[126:127], v[194:195] op_sel:[1,0,0] op_sel_hi:[1,1,0] neg_lo:[0,0,1] neg_hi:[0,0,1]
	v_pk_fma_f32 v[116:117], v[116:117], v[184:185], v[122:123]
	v_pk_fma_f32 v[122:123], v[224:225], v[192:193], v[194:195] op_sel:[1,0,0] op_sel_hi:[1,1,0] neg_lo:[0,0,1] neg_hi:[0,0,1]
	v_pk_fma_f32 v[124:125], v[164:165], v[124:125], v[172:173]
	v_pk_fma_f32 v[122:123], v[162:163], v[122:123], v[166:167]
	v_pk_fma_f32 v[112:113], v[112:113], v[170:171], v[124:125]
	v_pk_fma_f32 v[122:123], v[114:115], v[168:169], v[122:123]
	v_cvt_pk_bf16_f32 v114, v116, v117
	v_cvt_pk_bf16_f32 v116, v112, v113
; __device__ __forceinline__ u32x4 pack8f(f32x4 lo, f32x4 hi) { u32x4 w; w.x = cvtpk(lo[0], lo[1]); w.y = cvtpk(lo[2], lo[3]); w.z = cvtpk(hi[0], hi[1]); w.w = cvtpk(hi[2], hi[3]); return w; }
;     __device__ __forceinline__ void operator()(const Acc& acc, const Unit& u, int wr, int wc, int fr, int fq) const {
;     ...
;         for (int bj = 0; bj < 2; ++bj) {
;             f32x4 gm[2], G[2], Bc[2];
; #pragma unroll
;             for (int n = 0; n < 2; ++n) { const int c = col0 + bj * 128 + n * 4; gm[n] = *(const f32x4*)(gate + (size_t)b * NADA + c) + 1.0f; G[n] = *(const f32x4*)(lg + c) * ALPHA; Bc[n] = *(const f32x4*)(lb + c) * ALPHA; }
; #pragma unroll
;             for (int hf = 0; hf < 2; ++hf) {
;                 u32x4 yv[4]; f32x2 st[4];
; #pragma unroll
;                 for (int m = 0; m < 4; ++m) { const int row = rowb + hf * 128 + m * 16; yv[m] = *(const u32x4*)(y1 + yb + (size_t)(hf * 128 + m * 16) * 256 + bj * 128); st[m] = *(const f32x2*)(stats + (size_t)row * 2); }
; #pragma unroll
;                 for (int m = 0; m < 4; ++m) { const int row = rowb + hf * 128 + m * 16;
;                     f32x4 lo, hi; unpack8(yv[m], lo, hi); const float r = st[m][1], mr = st[m][0] * r;
;                     lo = (lo * r - mr) * G[0] + Bc[0] + gm[0] * acc[hf][bj][m][0]; hi = (hi * r - mr) * G[1] + Bc[1] + gm[1] * acc[hf][bj][m][1];
;                     *(u32x4*)(y2 + yb + (size_t)(hf * 128 + m * 16) * 256 + bj * 128) = pack8f(lo, hi); }
;                 asm volatile("" ::: "memory");
	v_add_co_u32_e32 v112, vcc, s66, v120
	v_cvt_pk_bf16_f32 v115, v118, v119
	v_cvt_pk_bf16_f32 v117, v122, v123
	v_addc_co_u32_e32 v113, vcc, 0, v121, vcc
	global_store_dwordx4 v[112:113], v[114:117], off
	v_pk_mul_f32 v[124:125], v[226:227], v[226:227] op_sel:[0,1] op_sel_hi:[1,0]
	v_lshlrev_b32_e32 v118, 16, v214
	v_lshlrev_b32_e32 v116, 16, v213
	v_and_b32_e32 v117, 0xffff0000, v213
	v_lshlrev_b32_e32 v114, 16, v212
	v_and_b32_e32 v115, 0xffff0000, v212
	v_pk_fma_f32 v[116:117], v[226:227], v[116:117], v[124:125] op_sel:[1,0,0] op_sel_hi:[1,1,0] neg_lo:[0,0,1] neg_hi:[0,0,1]
	v_and_b32_e32 v119, 0xffff0000, v214
	v_pk_fma_f32 v[114:115], v[226:227], v[114:115], v[124:125] op_sel:[1,0,0] op_sel_hi:[1,1,0] neg_lo:[0,0,1] neg_hi:[0,0,1]
	v_pk_fma_f32 v[116:117], v[174:175], v[116:117], v[178:179]
	v_lshlrev_b32_e32 v122, 16, v215
	v_and_b32_e32 v123, 0xffff0000, v215
	v_pk_fma_f32 v[114:115], v[176:177], v[114:115], v[180:181]
	v_pk_fma_f32 v[110:111], v[110:111], v[182:183], v[116:117]
	v_pk_fma_f32 v[116:117], v[226:227], v[118:119], v[124:125] op_sel:[1,0,0] op_sel_hi:[1,1,0] neg_lo:[0,0,1] neg_hi:[0,0,1]
	v_pk_fma_f32 v[108:109], v[108:109], v[184:185], v[114:115]
	v_pk_fma_f32 v[114:115], v[226:227], v[122:123], v[124:125] op_sel:[1,0,0] op_sel_hi:[1,1,0] neg_lo:[0,0,1] neg_hi:[0,0,1]
	v_pk_fma_f32 v[116:117], v[164:165], v[116:117], v[172:173]
	v_pk_fma_f32 v[114:115], v[162:163], v[114:115], v[166:167]
	v_pk_fma_f32 v[104:105], v[104:105], v[170:171], v[116:117]
	v_pk_fma_f32 v[114:115], v[106:107], v[168:169], v[114:115]
	v_cvt_pk_bf16_f32 v106, v108, v109
	v_cvt_pk_bf16_f32 v108, v104, v105
	v_add_co_u32_e32 v104, vcc, s67, v120
	v_cvt_pk_bf16_f32 v107, v110, v111
	v_cvt_pk_bf16_f32 v109, v114, v115
	v_addc_co_u32_e32 v105, vcc, 0, v121, vcc
	global_store_dwordx4 v[104:105], v[106:109], off
	v_pk_mul_f32 v[116:117], v[228:229], v[228:229] op_sel:[0,1] op_sel_hi:[1,0]
	v_lshlrev_b32_e32 v110, 16, v218
	v_lshlrev_b32_e32 v108, 16, v217
	v_and_b32_e32 v109, 0xffff0000, v217
	v_lshlrev_b32_e32 v106, 16, v216
	v_and_b32_e32 v107, 0xffff0000, v216
	v_pk_fma_f32 v[108:109], v[228:229], v[108:109], v[116:117] op_sel:[1,0,0] op_sel_hi:[1,1,0] neg_lo:[0,0,1] neg_hi:[0,0,1]
	v_and_b32_e32 v111, 0xffff0000, v218
	v_pk_fma_f32 v[106:107], v[228:229], v[106:107], v[116:117] op_sel:[1,0,0] op_sel_hi:[1,1,0] neg_lo:[0,0,1] neg_hi:[0,0,1]
	v_pk_fma_f32 v[108:109], v[174:175], v[108:109], v[178:179]
	v_lshlrev_b32_e32 v114, 16, v219
	v_and_b32_e32 v115, 0xffff0000, v219
	v_pk_fma_f32 v[106:107], v[176:177], v[106:107], v[180:181]
	v_pk_fma_f32 v[102:103], v[102:103], v[182:183], v[108:109]
	v_pk_fma_f32 v[108:109], v[228:229], v[110:111], v[116:117] op_sel:[1,0,0] op_sel_hi:[1,1,0] neg_lo:[0,0,1] neg_hi:[0,0,1]
	v_pk_fma_f32 v[100:101], v[100:101], v[184:185], v[106:107]
	v_pk_fma_f32 v[106:107], v[228:229], v[114:115], v[116:117] op_sel:[1,0,0] op_sel_hi:[1,1,0] neg_lo:[0,0,1] neg_hi:[0,0,1]
	v_pk_fma_f32 v[108:109], v[164:165], v[108:109], v[172:173]
	v_pk_fma_f32 v[106:107], v[162:163], v[106:107], v[166:167]
	v_pk_fma_f32 v[96:97], v[96:97], v[170:171], v[108:109]
	v_pk_fma_f32 v[106:107], v[98:99], v[168:169], v[106:107]
	v_cvt_pk_bf16_f32 v98, v100, v101
	v_cvt_pk_bf16_f32 v100, v96, v97
	v_add_co_u32_e32 v96, vcc, s68, v120
	v_cvt_pk_bf16_f32 v99, v102, v103
	v_cvt_pk_bf16_f32 v101, v106, v107
	v_addc_co_u32_e32 v97, vcc, 0, v121, vcc
	global_store_dwordx4 v[96:97], v[98:101], off
	s_mov_b32 s42, s36
	s_nop 0
	v_add_co_u32_e32 v98, vcc, s62, v148
	s_nop 1
	v_addc_co_u32_e32 v99, vcc, 0, v149, vcc
	s_waitcnt vmcnt(4)
	v_add_co_u32_e32 v100, vcc, s63, v148
	v_lshlrev_b32_e32 v200, 16, v230
	v_addc_co_u32_e32 v101, vcc, 0, v149, vcc
	v_add_co_u32_e32 v102, vcc, s64, v148
	v_and_b32_e32 v201, 0xffff0000, v230
	s_nop 0
	v_addc_co_u32_e32 v103, vcc, 0, v149, vcc
	v_add_co_u32_e32 v106, vcc, s65, v148
	v_lshlrev_b32_e32 v230, 16, v231
	s_nop 0
	v_addc_co_u32_e32 v107, vcc, 0, v149, vcc
	v_and_b32_e32 v231, 0xffff0000, v231
	v_pk_mul_f32 v[204:205], v[242:243], v[242:243] op_sel:[0,1] op_sel_hi:[1,0]
	v_lshlrev_b32_e32 v202, 16, v232
	v_pk_fma_f32 v[230:231], v[242:243], v[230:231], v[204:205] op_sel:[1,0,0] op_sel_hi:[1,1,0] neg_lo:[0,0,1] neg_hi:[0,0,1]
	v_and_b32_e32 v203, 0xffff0000, v232
	v_lshlrev_b32_e32 v232, 16, v233
	v_and_b32_e32 v233, 0xffff0000, v233
	v_pk_fma_f32 v[230:231], v[174:175], v[230:231], v[178:179]
	v_pk_fma_f32 v[200:201], v[242:243], v[200:201], v[204:205] op_sel:[1,0,0] op_sel_hi:[1,1,0] neg_lo:[0,0,1] neg_hi:[0,0,1]
	v_pk_fma_f32 v[94:95], v[94:95], v[182:183], v[230:231]
	v_pk_fma_f32 v[230:231], v[242:243], v[232:233], v[204:205] op_sel:[1,0,0] op_sel_hi:[1,1,0] neg_lo:[0,0,1] neg_hi:[0,0,1]
	v_pk_fma_f32 v[232:233], v[242:243], v[202:203], v[204:205] op_sel:[1,0,0] op_sel_hi:[1,1,0] neg_lo:[0,0,1] neg_hi:[0,0,1]
	v_pk_fma_f32 v[200:201], v[176:177], v[200:201], v[180:181]
	v_pk_fma_f32 v[232:233], v[164:165], v[232:233], v[172:173]
	v_pk_fma_f32 v[92:93], v[92:93], v[184:185], v[200:201]
	v_pk_fma_f32 v[230:231], v[162:163], v[230:231], v[166:167]
	v_pk_fma_f32 v[88:89], v[88:89], v[170:171], v[232:233]
	v_pk_fma_f32 v[230:231], v[90:91], v[168:169], v[230:231]
	v_cvt_pk_bf16_f32 v90, v92, v93
	v_cvt_pk_bf16_f32 v92, v88, v89
	v_add_co_u32_e32 v88, vcc, s62, v120
	v_cvt_pk_bf16_f32 v91, v94, v95
	v_cvt_pk_bf16_f32 v93, v230, v231
	v_addc_co_u32_e32 v89, vcc, 0, v121, vcc
	global_store_dwordx4 v[88:89], v[90:93], off
	v_lshlrev_b32_e32 v94, 16, v236
	v_lshlrev_b32_e32 v92, 16, v235
	v_and_b32_e32 v93, 0xffff0000, v235
	v_pk_mul_f32 v[232:233], v[250:251], v[250:251] op_sel:[0,1] op_sel_hi:[1,0]
	v_lshlrev_b32_e32 v90, 16, v234
; __device__ __forceinline__ u32x4 pack8f(f32x4 lo, f32x4 hi) { u32x4 w; w.x = cvtpk(lo[0], lo[1]); w.y = cvtpk(lo[2], lo[3]); w.z = cvtpk(hi[0], hi[1]); w.w = cvtpk(hi[2], hi[3]); return w; }
;     __device__ __forceinline__ void operator()(const Acc& acc, const Unit& u, int wr, int wc, int fr, int fq) const {
;     ...
;         for (int bj = 0; bj < 2; ++bj) {
;             f32x4 gm[2], G[2], Bc[2];
; #pragma unroll
;             for (int n = 0; n < 2; ++n) { const int c = col0 + bj * 128 + n * 4; gm[n] = *(const f32x4*)(gate + (size_t)b * NADA + c) + 1.0f; G[n] = *(const f32x4*)(lg + c) * ALPHA; Bc[n] = *(const f32x4*)(lb + c) * ALPHA; }
; #pragma unroll
;             for (int hf = 0; hf < 2; ++hf) {
;                 u32x4 yv[4]; f32x2 st[4];
; #pragma unroll
;                 for (int m = 0; m < 4; ++m) { const int row = rowb + hf * 128 + m * 16; yv[m] = *(const u32x4*)(y1 + yb + (size_t)(hf * 128 + m * 16) * 256 + bj * 128); st[m] = *(const f32x2*)(stats + (size_t)row * 2); }
; #pragma unroll
;                 for (int m = 0; m < 4; ++m) { const int row = rowb + hf * 128 + m * 16;
;                     f32x4 lo, hi; unpack8(yv[m], lo, hi); const float r = st[m][1], mr = st[m][0] * r;
;                     lo = (lo * r - mr) * G[0] + Bc[0] + gm[0] * acc[hf][bj][m][0]; hi = (hi * r - mr) * G[1] + Bc[1] + gm[1] * acc[hf][bj][m][1];
;                     *(u32x4*)(y2 + yb + (size_t)(hf * 128 + m * 16) * 256 + bj * 128) = pack8f(lo, hi); }
	v_and_b32_e32 v91, 0xffff0000, v234
	v_pk_fma_f32 v[92:93], v[250:251], v[92:93], v[232:233] op_sel:[1,0,0] op_sel_hi:[1,1,0] neg_lo:[0,0,1] neg_hi:[0,0,1]
	v_and_b32_e32 v95, 0xffff0000, v236
	v_pk_fma_f32 v[90:91], v[250:251], v[90:91], v[232:233] op_sel:[1,0,0] op_sel_hi:[1,1,0] neg_lo:[0,0,1] neg_hi:[0,0,1]
	v_pk_fma_f32 v[92:93], v[174:175], v[92:93], v[178:179]
	v_lshlrev_b32_e32 v230, 16, v237
	v_and_b32_e32 v231, 0xffff0000, v237
	v_pk_fma_f32 v[90:91], v[176:177], v[90:91], v[180:181]
	v_pk_fma_f32 v[86:87], v[86:87], v[182:183], v[92:93]
	v_pk_fma_f32 v[92:93], v[250:251], v[94:95], v[232:233] op_sel:[1,0,0] op_sel_hi:[1,1,0] neg_lo:[0,0,1] neg_hi:[0,0,1]
	v_pk_fma_f32 v[84:85], v[84:85], v[184:185], v[90:91]
	v_pk_fma_f32 v[90:91], v[250:251], v[230:231], v[232:233] op_sel:[1,0,0] op_sel_hi:[1,1,0] neg_lo:[0,0,1] neg_hi:[0,0,1]
	v_pk_fma_f32 v[92:93], v[164:165], v[92:93], v[172:173]
	v_pk_fma_f32 v[90:91], v[162:163], v[90:91], v[166:167]
	v_pk_fma_f32 v[80:81], v[80:81], v[170:171], v[92:93]
	v_pk_fma_f32 v[90:91], v[82:83], v[168:169], v[90:91]
	v_cvt_pk_bf16_f32 v82, v84, v85
	v_cvt_pk_bf16_f32 v84, v80, v81
	v_add_co_u32_e32 v80, vcc, s63, v120
	v_cvt_pk_bf16_f32 v83, v86, v87
	v_cvt_pk_bf16_f32 v85, v90, v91
	v_addc_co_u32_e32 v81, vcc, 0, v121, vcc
	global_store_dwordx4 v[80:81], v[82:85], off
	v_pk_mul_f32 v[92:93], v[252:253], v[252:253] op_sel:[0,1] op_sel_hi:[1,0]
	v_lshlrev_b32_e32 v86, 16, v240
	v_lshlrev_b32_e32 v84, 16, v239
	v_and_b32_e32 v85, 0xffff0000, v239
	v_lshlrev_b32_e32 v82, 16, v238
	v_and_b32_e32 v83, 0xffff0000, v238
	v_pk_fma_f32 v[84:85], v[252:253], v[84:85], v[92:93] op_sel:[1,0,0] op_sel_hi:[1,1,0] neg_lo:[0,0,1] neg_hi:[0,0,1]
	v_and_b32_e32 v87, 0xffff0000, v240
	v_pk_fma_f32 v[82:83], v[252:253], v[82:83], v[92:93] op_sel:[1,0,0] op_sel_hi:[1,1,0] neg_lo:[0,0,1] neg_hi:[0,0,1]
	v_pk_fma_f32 v[84:85], v[174:175], v[84:85], v[178:179]
	v_lshlrev_b32_e32 v90, 16, v241
	v_and_b32_e32 v91, 0xffff0000, v241
	v_pk_fma_f32 v[82:83], v[176:177], v[82:83], v[180:181]
	v_pk_fma_f32 v[78:79], v[78:79], v[182:183], v[84:85]
	v_pk_fma_f32 v[84:85], v[252:253], v[86:87], v[92:93] op_sel:[1,0,0] op_sel_hi:[1,1,0] neg_lo:[0,0,1] neg_hi:[0,0,1]
	v_pk_fma_f32 v[76:77], v[76:77], v[184:185], v[82:83]
	v_pk_fma_f32 v[82:83], v[252:253], v[90:91], v[92:93] op_sel:[1,0,0] op_sel_hi:[1,1,0] neg_lo:[0,0,1] neg_hi:[0,0,1]
	v_pk_fma_f32 v[84:85], v[164:165], v[84:85], v[172:173]
	v_pk_fma_f32 v[82:83], v[162:163], v[82:83], v[166:167]
	v_pk_fma_f32 v[72:73], v[72:73], v[170:171], v[84:85]
	v_pk_fma_f32 v[82:83], v[74:75], v[168:169], v[82:83]
	v_cvt_pk_bf16_f32 v74, v76, v77
	v_cvt_pk_bf16_f32 v76, v72, v73
	v_add_co_u32_e32 v72, vcc, s64, v120
	v_cvt_pk_bf16_f32 v75, v78, v79
	v_cvt_pk_bf16_f32 v77, v82, v83
	v_addc_co_u32_e32 v73, vcc, 0, v121, vcc
	global_store_dwordx4 v[72:73], v[74:77], off
	v_pk_mul_f32 v[84:85], v[254:255], v[254:255] op_sel:[0,1] op_sel_hi:[1,0]
	v_lshlrev_b32_e32 v78, 16, v248
	v_lshlrev_b32_e32 v76, 16, v247
	v_and_b32_e32 v77, 0xffff0000, v247
	v_lshlrev_b32_e32 v74, 16, v246
	v_and_b32_e32 v75, 0xffff0000, v246
	v_pk_fma_f32 v[76:77], v[254:255], v[76:77], v[84:85] op_sel:[1,0,0] op_sel_hi:[1,1,0] neg_lo:[0,0,1] neg_hi:[0,0,1]
	v_and_b32_e32 v79, 0xffff0000, v248
	v_pk_fma_f32 v[74:75], v[254:255], v[74:75], v[84:85] op_sel:[1,0,0] op_sel_hi:[1,1,0] neg_lo:[0,0,1] neg_hi:[0,0,1]
	v_pk_fma_f32 v[76:77], v[174:175], v[76:77], v[178:179]
	v_lshlrev_b32_e32 v82, 16, v249
	v_and_b32_e32 v83, 0xffff0000, v249
	v_pk_fma_f32 v[74:75], v[176:177], v[74:75], v[180:181]
	v_pk_fma_f32 v[70:71], v[70:71], v[182:183], v[76:77]
	v_pk_fma_f32 v[76:77], v[254:255], v[78:79], v[84:85] op_sel:[1,0,0] op_sel_hi:[1,1,0] neg_lo:[0,0,1] neg_hi:[0,0,1]
	v_pk_fma_f32 v[68:69], v[68:69], v[184:185], v[74:75]
	v_pk_fma_f32 v[74:75], v[254:255], v[82:83], v[84:85] op_sel:[1,0,0] op_sel_hi:[1,1,0] neg_lo:[0,0,1] neg_hi:[0,0,1]
	v_pk_fma_f32 v[76:77], v[164:165], v[76:77], v[172:173]
	v_pk_fma_f32 v[74:75], v[162:163], v[74:75], v[166:167]
	v_pk_fma_f32 v[64:65], v[64:65], v[170:171], v[76:77]
	v_pk_fma_f32 v[74:75], v[66:67], v[168:169], v[74:75]
	v_cvt_pk_bf16_f32 v66, v68, v69
	v_cvt_pk_bf16_f32 v68, v64, v65
	v_add_co_u32_e32 v64, vcc, s65, v120
	v_cvt_pk_bf16_f32 v67, v70, v71
	v_cvt_pk_bf16_f32 v69, v74, v75
	v_addc_co_u32_e32 v65, vcc, 0, v121, vcc
	global_store_dwordx4 v[64:65], v[66:69], off
	global_load_dwordx4 v[66:69], v[146:147], off offset:512
	global_load_dwordx4 v[82:85], v[142:143], off offset:512
	global_load_dwordx4 v[108:111], v[144:145], off offset:512
	global_load_dwordx4 v[114:117], v[146:147], off offset:528
	global_load_dwordx4 v[122:125], v[142:143], off offset:528
	s_nop 0
	global_load_dwordx4 v[142:145], v[144:145], off offset:528
	s_nop 0
	global_load_dwordx4 v[146:149], v[148:149], off offset:256
	s_nop 0
	global_load_dwordx2 v[118:119], v[140:141], off
	global_load_dwordx4 v[162:165], v[150:151], off offset:256
	global_load_dwordx2 v[126:127], v[152:153], off
	s_nop 0
	global_load_dwordx4 v[150:153], v[158:159], off offset:256
	s_nop 0
	global_load_dwordx2 v[158:159], v[160:161], off
	s_and_b64 vcc, exec, s[2:3]
	s_waitcnt vmcnt(11)
	v_pk_add_f32 v[74:75], v[68:69], 1.0 op_sel_hi:[1,0]
	v_pk_add_f32 v[76:77], v[66:67], 1.0 op_sel_hi:[1,0]
	s_waitcnt vmcnt(9)
	v_pk_mul_f32 v[92:93], v[110:111], s[28:29] op_sel_hi:[1,0]
	v_pk_mul_f32 v[94:95], v[108:109], s[28:29] op_sel_hi:[1,0]
	s_waitcnt vmcnt(8)
; __device__ __forceinline__ u32x4 pack8f(f32x4 lo, f32x4 hi) { u32x4 w; w.x = cvtpk(lo[0], lo[1]); w.y = cvtpk(lo[2], lo[3]); w.z = cvtpk(hi[0], hi[1]); w.w = cvtpk(hi[2], hi[3]); return w; }
;     __device__ __forceinline__ void operator()(const Acc& acc, const Unit& u, int wr, int wc, int fr, int fq) const {
;     ...
;         for (int bj = 0; bj < 2; ++bj) {
;             f32x4 gm[2], G[2], Bc[2];
; #pragma unroll
;             for (int n = 0; n < 2; ++n) { const int c = col0 + bj * 128 + n * 4; gm[n] = *(const f32x4*)(gate + (size_t)b * NADA + c) + 1.0f; G[n] = *(const f32x4*)(lg + c) * ALPHA; Bc[n] = *(const f32x4*)(lb + c) * ALPHA; }
; #pragma unroll
;             for (int hf = 0; hf < 2; ++hf) {
;                 u32x4 yv[4]; f32x2 st[4];
; #pragma unroll
;                 for (int m = 0; m < 4; ++m) { const int row = rowb + hf * 128 + m * 16; yv[m] = *(const u32x4*)(y1 + yb + (size_t)(hf * 128 + m * 16) * 256 + bj * 128); st[m] = *(const f32x2*)(stats + (size_t)row * 2); }
; #pragma unroll
;                 for (int m = 0; m < 4; ++m) { const int row = rowb + hf * 128 + m * 16;
;                     f32x4 lo, hi; unpack8(yv[m], lo, hi); const float r = st[m][1], mr = st[m][0] * r;
;                     lo = (lo * r - mr) * G[0] + Bc[0] + gm[0] * acc[hf][bj][m][0]; hi = (hi * r - mr) * G[1] + Bc[1] + gm[1] * acc[hf][bj][m][1];
;                     *(u32x4*)(y2 + yb + (size_t)(hf * 128 + m * 16) * 256 + bj * 128) = pack8f(lo, hi); }
	v_pk_add_f32 v[68:69], v[114:115], 1.0 op_sel_hi:[1,0]
	global_load_dwordx4 v[108:111], v[156:157], off offset:256
	global_load_dwordx2 v[114:115], v[154:155], off
	global_load_dwordx4 v[230:233], v[98:99], off offset:256
	global_load_dwordx2 v[242:243], v[140:141], off offset:1024
	global_load_dwordx4 v[234:237], v[100:101], off offset:256
	global_load_dwordx2 v[250:251], v[140:141], off offset:1152
	global_load_dwordx4 v[238:241], v[102:103], off offset:256
	global_load_dwordx2 v[252:253], v[140:141], off offset:1280
	global_load_dwordx4 v[246:249], v[106:107], off offset:256
	global_load_dwordx2 v[254:255], v[140:141], off offset:1408
	v_pk_mul_f32 v[90:91], v[82:83], s[28:29] op_sel_hi:[1,0]
	v_pk_add_f32 v[66:67], v[116:117], 1.0 op_sel_hi:[1,0]
	s_waitcnt vmcnt(16)
	v_pk_mul_f32 v[82:83], v[144:145], s[28:29] op_sel_hi:[1,0]
	s_waitcnt vmcnt(15)
	v_lshlrev_b32_e32 v116, 16, v146
	v_and_b32_e32 v117, 0xffff0000, v146
	s_waitcnt vmcnt(14)
	v_pk_mul_f32 v[144:145], v[118:119], v[118:119] op_sel:[0,1] op_sel_hi:[1,0]
	v_pk_mul_f32 v[86:87], v[84:85], s[28:29] op_sel_hi:[1,0]
	v_pk_fma_f32 v[116:117], v[118:119], v[116:117], v[144:145] op_sel:[1,0,0] op_sel_hi:[1,1,0] neg_lo:[0,0,1] neg_hi:[0,0,1]
	v_pk_mul_f32 v[70:71], v[124:125], s[28:29] op_sel_hi:[1,0]
	v_pk_mul_f32 v[78:79], v[122:123], s[28:29] op_sel_hi:[1,0]
	v_pk_mul_f32 v[84:85], v[142:143], s[28:29] op_sel_hi:[1,0]
	v_lshlrev_b32_e32 v122, 16, v147
	v_and_b32_e32 v123, 0xffff0000, v147
	v_lshlrev_b32_e32 v124, 16, v148
	v_and_b32_e32 v125, 0xffff0000, v148
	v_lshlrev_b32_e32 v142, 16, v149
	v_and_b32_e32 v143, 0xffff0000, v149
	v_pk_fma_f32 v[116:117], v[90:91], v[116:117], v[94:95]
	v_pk_fma_f32 v[122:123], v[118:119], v[122:123], v[144:145] op_sel:[1,0,0] op_sel_hi:[1,1,0] neg_lo:[0,0,1] neg_hi:[0,0,1]
	v_pk_fma_f32 v[60:61], v[60:61], v[76:77], v[116:117]
	v_pk_fma_f32 v[116:117], v[118:119], v[124:125], v[144:145] op_sel:[1,0,0] op_sel_hi:[1,1,0] neg_lo:[0,0,1] neg_hi:[0,0,1]
	v_pk_fma_f32 v[118:119], v[118:119], v[142:143], v[144:145] op_sel:[1,0,0] op_sel_hi:[1,1,0] neg_lo:[0,0,1] neg_hi:[0,0,1]
	v_pk_fma_f32 v[122:123], v[86:87], v[122:123], v[92:93]
	v_pk_fma_f32 v[118:119], v[70:71], v[118:119], v[82:83]
	v_pk_fma_f32 v[116:117], v[78:79], v[116:117], v[84:85]
	v_pk_fma_f32 v[62:63], v[62:63], v[74:75], v[122:123]
	v_pk_fma_f32 v[118:119], v[58:59], v[66:67], v[118:119]
	v_pk_fma_f32 v[58:59], v[56:57], v[68:69], v[116:117]
	v_cvt_pk_bf16_f32 v56, v60, v61
	v_cvt_pk_bf16_f32 v57, v62, v63
	v_cvt_pk_bf16_f32 v58, v58, v59
	v_cvt_pk_bf16_f32 v59, v118, v119
	global_store_dwordx4 v[120:121], v[56:59], off offset:256
	s_waitcnt vmcnt(13)
	v_pk_mul_f32 v[116:117], v[126:127], v[126:127] op_sel:[0,1] op_sel_hi:[1,0]
	v_lshlrev_b32_e32 v60, 16, v164
	v_lshlrev_b32_e32 v56, 16, v162
	v_and_b32_e32 v57, 0xffff0000, v162
	v_lshlrev_b32_e32 v58, 16, v163
	v_and_b32_e32 v59, 0xffff0000, v163
	v_pk_fma_f32 v[58:59], v[126:127], v[58:59], v[116:117] op_sel:[1,0,0] op_sel_hi:[1,1,0] neg_lo:[0,0,1] neg_hi:[0,0,1]
	v_pk_fma_f32 v[56:57], v[126:127], v[56:57], v[116:117] op_sel:[1,0,0] op_sel_hi:[1,1,0] neg_lo:[0,0,1] neg_hi:[0,0,1]
	v_and_b32_e32 v61, 0xffff0000, v164
	v_lshlrev_b32_e32 v62, 16, v165
	v_and_b32_e32 v63, 0xffff0000, v165
	v_pk_fma_f32 v[56:57], v[90:91], v[56:57], v[94:95]
	v_pk_fma_f32 v[58:59], v[86:87], v[58:59], v[92:93]
	v_pk_fma_f32 v[52:53], v[52:53], v[76:77], v[56:57]
	v_pk_fma_f32 v[54:55], v[54:55], v[74:75], v[58:59]
	v_pk_fma_f32 v[56:57], v[126:127], v[62:63], v[116:117] op_sel:[1,0,0] op_sel_hi:[1,1,0] neg_lo:[0,0,1] neg_hi:[0,0,1]
	v_pk_fma_f32 v[58:59], v[126:127], v[60:61], v[116:117] op_sel:[1,0,0] op_sel_hi:[1,1,0] neg_lo:[0,0,1] neg_hi:[0,0,1]
	v_pk_fma_f32 v[56:57], v[70:71], v[56:57], v[82:83]
	v_pk_fma_f32 v[58:59], v[78:79], v[58:59], v[84:85]
	v_pk_fma_f32 v[56:57], v[50:51], v[66:67], v[56:57]
	v_pk_fma_f32 v[50:51], v[48:49], v[68:69], v[58:59]
	v_cvt_pk_bf16_f32 v48, v52, v53
	v_cvt_pk_bf16_f32 v49, v54, v55
	v_cvt_pk_bf16_f32 v50, v50, v51
	v_cvt_pk_bf16_f32 v51, v56, v57
	global_store_dwordx4 v[112:113], v[48:51], off offset:256
	s_waitcnt vmcnt(12)
	v_pk_mul_f32 v[56:57], v[158:159], v[158:159] op_sel:[0,1] op_sel_hi:[1,0]
	v_lshlrev_b32_e32 v52, 16, v152
	v_lshlrev_b32_e32 v48, 16, v150
	v_and_b32_e32 v49, 0xffff0000, v150
	v_lshlrev_b32_e32 v50, 16, v151
	v_and_b32_e32 v51, 0xffff0000, v151
	v_pk_fma_f32 v[50:51], v[158:159], v[50:51], v[56:57] op_sel:[1,0,0] op_sel_hi:[1,1,0] neg_lo:[0,0,1] neg_hi:[0,0,1]
	v_pk_fma_f32 v[48:49], v[158:159], v[48:49], v[56:57] op_sel:[1,0,0] op_sel_hi:[1,1,0] neg_lo:[0,0,1] neg_hi:[0,0,1]
	v_and_b32_e32 v53, 0xffff0000, v152
	v_lshlrev_b32_e32 v54, 16, v153
	v_and_b32_e32 v55, 0xffff0000, v153
	v_pk_fma_f32 v[48:49], v[90:91], v[48:49], v[94:95]
	v_pk_fma_f32 v[50:51], v[86:87], v[50:51], v[92:93]
	v_pk_fma_f32 v[44:45], v[44:45], v[76:77], v[48:49]
	v_pk_fma_f32 v[46:47], v[46:47], v[74:75], v[50:51]
	v_pk_fma_f32 v[48:49], v[158:159], v[54:55], v[56:57] op_sel:[1,0,0] op_sel_hi:[1,1,0] neg_lo:[0,0,1] neg_hi:[0,0,1]
	v_pk_fma_f32 v[50:51], v[158:159], v[52:53], v[56:57] op_sel:[1,0,0] op_sel_hi:[1,1,0] neg_lo:[0,0,1] neg_hi:[0,0,1]
	v_pk_fma_f32 v[48:49], v[70:71], v[48:49], v[82:83]
	v_pk_fma_f32 v[50:51], v[78:79], v[50:51], v[84:85]
	v_pk_fma_f32 v[48:49], v[42:43], v[66:67], v[48:49]
	v_pk_fma_f32 v[42:43], v[40:41], v[68:69], v[50:51]
	v_cvt_pk_bf16_f32 v40, v44, v45
	v_cvt_pk_bf16_f32 v41, v46, v47
	v_cvt_pk_bf16_f32 v42, v42, v43
	v_cvt_pk_bf16_f32 v43, v48, v49
	global_store_dwordx4 v[104:105], v[40:43], off offset:256
	s_waitcnt vmcnt(11)
; __device__ __forceinline__ u32x4 pack8f(f32x4 lo, f32x4 hi) { u32x4 w; w.x = cvtpk(lo[0], lo[1]); w.y = cvtpk(lo[2], lo[3]); w.z = cvtpk(hi[0], hi[1]); w.w = cvtpk(hi[2], hi[3]); return w; }
;     __device__ __forceinline__ void operator()(const Acc& acc, const Unit& u, int wr, int wc, int fr, int fq) const {
;     ...
;             for (int hf = 0; hf < 2; ++hf) {
;                 u32x4 yv[4]; f32x2 st[4];
; #pragma unroll
;                 for (int m = 0; m < 4; ++m) { const int row = rowb + hf * 128 + m * 16; yv[m] = *(const u32x4*)(y1 + yb + (size_t)(hf * 128 + m * 16) * 256 + bj * 128); st[m] = *(const f32x2*)(stats + (size_t)row * 2); }
; #pragma unroll
;                 for (int m = 0; m < 4; ++m) { const int row = rowb + hf * 128 + m * 16;
;                     f32x4 lo, hi; unpack8(yv[m], lo, hi); const float r = st[m][1], mr = st[m][0] * r;
;                     lo = (lo * r - mr) * G[0] + Bc[0] + gm[0] * acc[hf][bj][m][0]; hi = (hi * r - mr) * G[1] + Bc[1] + gm[1] * acc[hf][bj][m][1];
;                     *(u32x4*)(y2 + yb + (size_t)(hf * 128 + m * 16) * 256 + bj * 128) = pack8f(lo, hi); }
	v_pk_mul_f32 v[48:49], v[114:115], v[114:115] op_sel:[0,1] op_sel_hi:[1,0]
	v_lshlrev_b32_e32 v44, 16, v110
	v_lshlrev_b32_e32 v40, 16, v108
	v_and_b32_e32 v41, 0xffff0000, v108
	v_lshlrev_b32_e32 v42, 16, v109
	v_and_b32_e32 v43, 0xffff0000, v109
	v_pk_fma_f32 v[42:43], v[114:115], v[42:43], v[48:49] op_sel:[1,0,0] op_sel_hi:[1,1,0] neg_lo:[0,0,1] neg_hi:[0,0,1]
	v_pk_fma_f32 v[40:41], v[114:115], v[40:41], v[48:49] op_sel:[1,0,0] op_sel_hi:[1,1,0] neg_lo:[0,0,1] neg_hi:[0,0,1]
	v_and_b32_e32 v45, 0xffff0000, v110
	v_lshlrev_b32_e32 v46, 16, v111
	v_and_b32_e32 v47, 0xffff0000, v111
	v_pk_fma_f32 v[40:41], v[90:91], v[40:41], v[94:95]
	v_pk_fma_f32 v[42:43], v[86:87], v[42:43], v[92:93]
	v_pk_fma_f32 v[36:37], v[36:37], v[76:77], v[40:41]
	v_pk_fma_f32 v[38:39], v[38:39], v[74:75], v[42:43]
	v_pk_fma_f32 v[40:41], v[114:115], v[46:47], v[48:49] op_sel:[1,0,0] op_sel_hi:[1,1,0] neg_lo:[0,0,1] neg_hi:[0,0,1]
	v_pk_fma_f32 v[42:43], v[114:115], v[44:45], v[48:49] op_sel:[1,0,0] op_sel_hi:[1,1,0] neg_lo:[0,0,1] neg_hi:[0,0,1]
	v_pk_fma_f32 v[40:41], v[70:71], v[40:41], v[82:83]
	v_pk_fma_f32 v[42:43], v[78:79], v[42:43], v[84:85]
	v_pk_fma_f32 v[40:41], v[34:35], v[66:67], v[40:41]
	v_pk_fma_f32 v[34:35], v[32:33], v[68:69], v[42:43]
	v_cvt_pk_bf16_f32 v32, v36, v37
	v_cvt_pk_bf16_f32 v33, v38, v39
	v_cvt_pk_bf16_f32 v34, v34, v35
	v_cvt_pk_bf16_f32 v35, v40, v41
	global_store_dwordx4 v[96:97], v[32:35], off offset:256
	s_waitcnt vmcnt(4)
; __device__ __forceinline__ u32x4 pack8f(f32x4 lo, f32x4 hi) { u32x4 w; w.x = cvtpk(lo[0], lo[1]); w.y = cvtpk(lo[2], lo[3]); w.z = cvtpk(hi[0], hi[1]); w.w = cvtpk(hi[2], hi[3]); return w; }
;     __device__ __forceinline__ void operator()(const Acc& acc, const Unit& u, int wr, int wc, int fr, int fq) const {
;     ...
;             for (int hf = 0; hf < 2; ++hf) {
;                 u32x4 yv[4]; f32x2 st[4];
; #pragma unroll
;                 for (int m = 0; m < 4; ++m) { const int row = rowb + hf * 128 + m * 16; yv[m] = *(const u32x4*)(y1 + yb + (size_t)(hf * 128 + m * 16) * 256 + bj * 128); st[m] = *(const f32x2*)(stats + (size_t)row * 2); }
; #pragma unroll
;                 for (int m = 0; m < 4; ++m) { const int row = rowb + hf * 128 + m * 16;
;                     f32x4 lo, hi; unpack8(yv[m], lo, hi); const float r = st[m][1], mr = st[m][0] * r;
;                     lo = (lo * r - mr) * G[0] + Bc[0] + gm[0] * acc[hf][bj][m][0]; hi = (hi * r - mr) * G[1] + Bc[1] + gm[1] * acc[hf][bj][m][1];
;                     *(u32x4*)(y2 + yb + (size_t)(hf * 128 + m * 16) * 256 + bj * 128) = pack8f(lo, hi); }
;                 asm volatile("" ::: "memory");
;             }
;             asm volatile("" ::: "memory");
	v_lshlrev_b32_e32 v56, 16, v230
	v_and_b32_e32 v57, 0xffff0000, v230
	v_lshlrev_b32_e32 v230, 16, v231
	v_and_b32_e32 v231, 0xffff0000, v231
	v_pk_mul_f32 v[60:61], v[242:243], v[242:243] op_sel:[0,1] op_sel_hi:[1,0]
	v_lshlrev_b32_e32 v58, 16, v232
	v_pk_fma_f32 v[230:231], v[242:243], v[230:231], v[60:61] op_sel:[1,0,0] op_sel_hi:[1,1,0] neg_lo:[0,0,1] neg_hi:[0,0,1]
	v_and_b32_e32 v59, 0xffff0000, v232
	v_lshlrev_b32_e32 v232, 16, v233
	v_and_b32_e32 v233, 0xffff0000, v233
	v_pk_fma_f32 v[230:231], v[86:87], v[230:231], v[92:93]
	v_pk_fma_f32 v[56:57], v[242:243], v[56:57], v[60:61] op_sel:[1,0,0] op_sel_hi:[1,1,0] neg_lo:[0,0,1] neg_hi:[0,0,1]
	v_pk_fma_f32 v[30:31], v[30:31], v[74:75], v[230:231]
	v_pk_fma_f32 v[230:231], v[242:243], v[232:233], v[60:61] op_sel:[1,0,0] op_sel_hi:[1,1,0] neg_lo:[0,0,1] neg_hi:[0,0,1]
	v_pk_fma_f32 v[232:233], v[242:243], v[58:59], v[60:61] op_sel:[1,0,0] op_sel_hi:[1,1,0] neg_lo:[0,0,1] neg_hi:[0,0,1]
	v_pk_fma_f32 v[56:57], v[90:91], v[56:57], v[94:95]
	v_pk_fma_f32 v[232:233], v[78:79], v[232:233], v[84:85]
	v_pk_fma_f32 v[230:231], v[70:71], v[230:231], v[82:83]
	v_pk_fma_f32 v[28:29], v[28:29], v[76:77], v[56:57]
	v_pk_fma_f32 v[230:231], v[26:27], v[66:67], v[230:231]
	v_pk_fma_f32 v[26:27], v[24:25], v[68:69], v[232:233]
	v_cvt_pk_bf16_f32 v24, v28, v29
	v_cvt_pk_bf16_f32 v25, v30, v31
	v_cvt_pk_bf16_f32 v26, v26, v27
	v_cvt_pk_bf16_f32 v27, v230, v231
	global_store_dwordx4 v[88:89], v[24:27], off offset:256
	v_pk_mul_f32 v[230:231], v[250:251], v[250:251] op_sel:[0,1] op_sel_hi:[1,0]
	v_lshlrev_b32_e32 v28, 16, v236
	v_lshlrev_b32_e32 v24, 16, v234
	v_and_b32_e32 v25, 0xffff0000, v234
	v_lshlrev_b32_e32 v26, 16, v235
	v_and_b32_e32 v27, 0xffff0000, v235
	v_pk_fma_f32 v[26:27], v[250:251], v[26:27], v[230:231] op_sel:[1,0,0] op_sel_hi:[1,1,0] neg_lo:[0,0,1] neg_hi:[0,0,1]
	v_pk_fma_f32 v[24:25], v[250:251], v[24:25], v[230:231] op_sel:[1,0,0] op_sel_hi:[1,1,0] neg_lo:[0,0,1] neg_hi:[0,0,1]
	v_and_b32_e32 v29, 0xffff0000, v236
	v_lshlrev_b32_e32 v30, 16, v237
	v_and_b32_e32 v31, 0xffff0000, v237
	v_pk_fma_f32 v[24:25], v[90:91], v[24:25], v[94:95]
	v_pk_fma_f32 v[26:27], v[86:87], v[26:27], v[92:93]
	v_pk_fma_f32 v[20:21], v[20:21], v[76:77], v[24:25]
	v_pk_fma_f32 v[22:23], v[22:23], v[74:75], v[26:27]
	v_pk_fma_f32 v[24:25], v[250:251], v[30:31], v[230:231] op_sel:[1,0,0] op_sel_hi:[1,1,0] neg_lo:[0,0,1] neg_hi:[0,0,1]
	v_pk_fma_f32 v[26:27], v[250:251], v[28:29], v[230:231] op_sel:[1,0,0] op_sel_hi:[1,1,0] neg_lo:[0,0,1] neg_hi:[0,0,1]
	v_pk_fma_f32 v[24:25], v[70:71], v[24:25], v[82:83]
	v_pk_fma_f32 v[26:27], v[78:79], v[26:27], v[84:85]
	v_pk_fma_f32 v[24:25], v[18:19], v[66:67], v[24:25]
	v_pk_fma_f32 v[18:19], v[16:17], v[68:69], v[26:27]
	v_cvt_pk_bf16_f32 v16, v20, v21
	v_cvt_pk_bf16_f32 v17, v22, v23
	v_cvt_pk_bf16_f32 v18, v18, v19
	v_cvt_pk_bf16_f32 v19, v24, v25
	global_store_dwordx4 v[80:81], v[16:19], off offset:256
	v_pk_mul_f32 v[24:25], v[252:253], v[252:253] op_sel:[0,1] op_sel_hi:[1,0]
	v_lshlrev_b32_e32 v20, 16, v240
	v_lshlrev_b32_e32 v16, 16, v238
	v_and_b32_e32 v17, 0xffff0000, v238
	v_lshlrev_b32_e32 v18, 16, v239
	v_and_b32_e32 v19, 0xffff0000, v239
	v_pk_fma_f32 v[18:19], v[252:253], v[18:19], v[24:25] op_sel:[1,0,0] op_sel_hi:[1,1,0] neg_lo:[0,0,1] neg_hi:[0,0,1]
	v_pk_fma_f32 v[16:17], v[252:253], v[16:17], v[24:25] op_sel:[1,0,0] op_sel_hi:[1,1,0] neg_lo:[0,0,1] neg_hi:[0,0,1]
	v_and_b32_e32 v21, 0xffff0000, v240
	v_lshlrev_b32_e32 v22, 16, v241
	v_and_b32_e32 v23, 0xffff0000, v241
	v_pk_fma_f32 v[16:17], v[90:91], v[16:17], v[94:95]
	v_pk_fma_f32 v[18:19], v[86:87], v[18:19], v[92:93]
	v_pk_fma_f32 v[12:13], v[12:13], v[76:77], v[16:17]
	v_pk_fma_f32 v[14:15], v[14:15], v[74:75], v[18:19]
	v_pk_fma_f32 v[16:17], v[252:253], v[22:23], v[24:25] op_sel:[1,0,0] op_sel_hi:[1,1,0] neg_lo:[0,0,1] neg_hi:[0,0,1]
	v_pk_fma_f32 v[18:19], v[252:253], v[20:21], v[24:25] op_sel:[1,0,0] op_sel_hi:[1,1,0] neg_lo:[0,0,1] neg_hi:[0,0,1]
	v_pk_fma_f32 v[16:17], v[70:71], v[16:17], v[82:83]
	v_pk_fma_f32 v[18:19], v[78:79], v[18:19], v[84:85]
	v_pk_fma_f32 v[16:17], v[10:11], v[66:67], v[16:17]
	v_pk_fma_f32 v[10:11], v[8:9], v[68:69], v[18:19]
	v_cvt_pk_bf16_f32 v8, v12, v13
	v_cvt_pk_bf16_f32 v9, v14, v15
	v_cvt_pk_bf16_f32 v10, v10, v11
	v_cvt_pk_bf16_f32 v11, v16, v17
	global_store_dwordx4 v[72:73], v[8:11], off offset:256
	v_pk_mul_f32 v[16:17], v[254:255], v[254:255] op_sel:[0,1] op_sel_hi:[1,0]
	v_lshlrev_b32_e32 v12, 16, v248
	v_lshlrev_b32_e32 v8, 16, v246
	v_and_b32_e32 v9, 0xffff0000, v246
	v_lshlrev_b32_e32 v10, 16, v247
	v_and_b32_e32 v11, 0xffff0000, v247
	v_pk_fma_f32 v[10:11], v[254:255], v[10:11], v[16:17] op_sel:[1,0,0] op_sel_hi:[1,1,0] neg_lo:[0,0,1] neg_hi:[0,0,1]
	v_pk_fma_f32 v[8:9], v[254:255], v[8:9], v[16:17] op_sel:[1,0,0] op_sel_hi:[1,1,0] neg_lo:[0,0,1] neg_hi:[0,0,1]
	v_and_b32_e32 v13, 0xffff0000, v248
	v_lshlrev_b32_e32 v14, 16, v249
	v_and_b32_e32 v15, 0xffff0000, v249
	v_pk_fma_f32 v[8:9], v[90:91], v[8:9], v[94:95]
	v_pk_fma_f32 v[10:11], v[86:87], v[10:11], v[92:93]
	v_pk_fma_f32 v[4:5], v[4:5], v[76:77], v[8:9]
	v_pk_fma_f32 v[6:7], v[6:7], v[74:75], v[10:11]
	v_pk_fma_f32 v[8:9], v[254:255], v[14:15], v[16:17] op_sel:[1,0,0] op_sel_hi:[1,1,0] neg_lo:[0,0,1] neg_hi:[0,0,1]
	v_pk_fma_f32 v[10:11], v[254:255], v[12:13], v[16:17] op_sel:[1,0,0] op_sel_hi:[1,1,0] neg_lo:[0,0,1] neg_hi:[0,0,1]
	v_pk_fma_f32 v[8:9], v[70:71], v[8:9], v[82:83]
	v_pk_fma_f32 v[10:11], v[78:79], v[10:11], v[84:85]
	v_pk_fma_f32 v[8:9], v[2:3], v[66:67], v[8:9]
	v_pk_fma_f32 v[2:3], v[0:1], v[68:69], v[10:11]
	v_cvt_pk_bf16_f32 v0, v4, v5
	v_cvt_pk_bf16_f32 v1, v6, v7
	v_cvt_pk_bf16_f32 v2, v2, v3
	v_cvt_pk_bf16_f32 v3, v8, v9
	global_store_dwordx4 v[64:65], v[0:3], off offset:256
	s_cbranch_vccz .LBB0_1274
	s_waitcnt vmcnt(0)
	s_cmpk_gt_u32 s29, 0xff
	s_cbranch_scc1 .LBB0_1285
	s_barrier
